# ssd G-mask epilogue: 16 conditional serialized ds_read_b32 of sAc replaced by four ds_read_b128 preloads (wait placed before the register copies)
# speedup vs baseline: 1.0132x; 1.0022x over previous
.LBB0_539:
	s_or_b64 exec, exec, s[0:1]
	v_and_b32_e32 v16, 48, v1
	s_movk_i32 s2, 0x110
	v_mad_u32_u24 v19, v17, s2, v16
	s_waitcnt lgkmcnt(0)
	s_barrier
	ds_read_b128 v[4:7], v19
	ds_read_b128 v[8:11], v19 offset:4352
	s_waitcnt vmcnt(8)
	ds_read_b128 v[12:15], v19 offset:8704
	ds_read_b128 v[22:25], v19 offset:13056
	v_ashrrev_i32_e32 v0, 2, v1
	v_and_or_b32 v18, v0, -16, v17
	v_mad_u64_u32 v[30:31], s[0:1], v18, s2, v[16:17]
	s_waitcnt vmcnt(2)
	v_lshrrev_b32_e32 v20, 4, v3
	ds_read_b128 v[0:3], v30 offset:17408
	s_waitcnt lgkmcnt(0)
	v_mfma_f32_16x16x32_bf16 v[4:7], v[4:7], v[0:3], 0
	v_mfma_f32_16x16x32_bf16 v[8:11], v[8:11], v[0:3], 0
	v_mfma_f32_16x16x32_bf16 v[12:15], v[12:15], v[0:3], 0
	v_mfma_f32_16x16x32_bf16 v[0:3], v[22:25], v[0:3], 0
	ds_read_b128 v[22:25], v30 offset:17472
	ds_read_b128 v[26:29], v19 offset:64
	s_waitcnt lgkmcnt(0)
	v_mfma_f32_16x16x32_bf16 v[4:7], v[26:29], v[22:25], v[4:7]
	ds_read_b128 v[26:29], v19 offset:4416
	s_waitcnt lgkmcnt(0)
	v_mfma_f32_16x16x32_bf16 v[8:11], v[26:29], v[22:25], v[8:11]
	ds_read_b128 v[26:29], v19 offset:8768
	s_waitcnt lgkmcnt(0)
	v_mfma_f32_16x16x32_bf16 v[12:15], v[26:29], v[22:25], v[12:15]
	ds_read_b128 v[26:29], v19 offset:13120
	s_waitcnt lgkmcnt(0)
	v_mfma_f32_16x16x32_bf16 v[0:3], v[26:29], v[22:25], v[0:3]
	ds_read_b128 v[22:25], v30 offset:17536
	ds_read_b128 v[26:29], v19 offset:128
	s_waitcnt lgkmcnt(0)
	v_mfma_f32_16x16x32_bf16 v[4:7], v[26:29], v[22:25], v[4:7]
	ds_read_b128 v[26:29], v19 offset:4480
	s_waitcnt lgkmcnt(0)
	v_mfma_f32_16x16x32_bf16 v[8:11], v[26:29], v[22:25], v[8:11]
	ds_read_b128 v[26:29], v19 offset:8832
	s_waitcnt lgkmcnt(0)
	v_mfma_f32_16x16x32_bf16 v[26:29], v[26:29], v[22:25], v[12:15]
	s_nop 2
	ds_read_b128 v[12:15], v19 offset:13184
	s_waitcnt lgkmcnt(0)
	v_mfma_f32_16x16x32_bf16 v[0:3], v[12:15], v[22:25], v[0:3]
	ds_read_b128 v[22:25], v30 offset:17600
	ds_read_b128 v[12:15], v19 offset:192
	s_waitcnt lgkmcnt(0)
	v_mfma_f32_16x16x32_bf16 v[12:15], v[12:15], v[22:25], v[4:7]
	s_nop 2
	ds_read_b128 v[4:7], v19 offset:4544
	s_waitcnt lgkmcnt(0)
	v_mfma_f32_16x16x32_bf16 v[8:11], v[4:7], v[22:25], v[8:11]
	ds_read_b128 v[4:7], v19 offset:8896
	s_waitcnt lgkmcnt(0)
	v_mfma_f32_16x16x32_bf16 v[4:7], v[4:7], v[22:25], v[26:29]
	s_nop 2
	ds_read_b128 v[26:29], v19 offset:13248
	v_lshlrev_b32_e32 v19, 2, v18
	ds_read_b32 v21, v19 offset:62464
	s_waitcnt lgkmcnt(1)
	v_mfma_f32_16x16x32_bf16 v[0:3], v[26:29], v[22:25], v[0:3]
	v_lshlrev_b32_e32 v19, 2, v20
	v_cmp_ge_i32_e32 vcc, v18, v19
	v_mov_b32_e32 v22, 0
	v_lshlrev_b32_e32 v136, 2, v19
	ds_read_b128 v[204:207], v136 offset:62464
	ds_read_b128 v[208:211], v136 offset:62528
	ds_read_b128 v[212:215], v136 offset:62592
	ds_read_b128 v[216:219], v136 offset:62656
	v_mov_b32_e32 v23, 0
	s_and_saveexec_b64 s[0:1], vcc
	s_cbranch_execz .LBB0_541
	s_waitcnt lgkmcnt(0)
	v_mov_b32_e32 v23, v204
	s_waitcnt lgkmcnt(0)
	v_sub_f32_e32 v23, v21, v23
	v_mul_f32_e32 v23, 0x3fb8aa3b, v23
	v_exp_f32_e32 v23, v23
	s_nop 0
	v_mul_f32_e32 v23, v12, v23
.LBB0_541:
	s_or_b64 exec, exec, s[0:1]
	v_cmp_gt_i32_e32 vcc, v18, v19
	v_mov_b32_e32 v12, 0
	s_and_saveexec_b64 s[0:1], vcc
	s_cbranch_execz .LBB0_543
	s_waitcnt lgkmcnt(0)
	v_mov_b32_e32 v12, v205
	s_waitcnt lgkmcnt(0)
	v_sub_f32_e32 v12, v21, v12
	v_mul_f32_e32 v12, 0x3fb8aa3b, v12
	v_exp_f32_e32 v12, v12
	s_nop 0
	v_mul_f32_e32 v12, v13, v12
.LBB0_543:
	s_or_b64 exec, exec, s[0:1]
	v_or_b32_e32 v13, 2, v19
	v_cmp_ge_i32_e32 vcc, v18, v13
	s_and_saveexec_b64 s[0:1], vcc
	s_cbranch_execz .LBB0_545
	s_waitcnt lgkmcnt(0)
	v_mov_b32_e32 v13, v206
	s_waitcnt lgkmcnt(0)
	v_sub_f32_e32 v13, v21, v13
	v_mul_f32_e32 v13, 0x3fb8aa3b, v13
	v_exp_f32_e32 v13, v13
	s_nop 0
	v_mul_f32_e32 v22, v14, v13
.LBB0_545:
	s_or_b64 exec, exec, s[0:1]
	v_or_b32_e32 v13, 3, v19
	v_cmp_ge_i32_e32 vcc, v18, v13
	v_mov_b32_e32 v13, 0
	v_mov_b32_e32 v14, 0
	s_and_saveexec_b64 s[0:1], vcc
	s_cbranch_execz .LBB0_547
	s_waitcnt lgkmcnt(0)
	v_mov_b32_e32 v14, v207
	s_waitcnt lgkmcnt(0)
	v_sub_f32_e32 v14, v21, v14
	v_mul_f32_e32 v14, 0x3fb8aa3b, v14
	v_exp_f32_e32 v14, v14
	s_nop 0
	v_mul_f32_e32 v14, v15, v14
.LBB0_547:
	s_or_b64 exec, exec, s[0:1]
	v_or_b32_e32 v15, 16, v19
	v_cmp_ge_i32_e32 vcc, v18, v15
	s_and_saveexec_b64 s[0:1], vcc
	s_cbranch_execz .LBB0_549
	s_waitcnt lgkmcnt(0)
	v_mov_b32_e32 v13, v208
	s_waitcnt lgkmcnt(0)
	v_sub_f32_e32 v13, v21, v13
	v_mul_f32_e32 v13, 0x3fb8aa3b, v13
	v_exp_f32_e32 v13, v13
	s_nop 0
	v_mul_f32_e32 v13, v8, v13
.LBB0_549:
	s_or_b64 exec, exec, s[0:1]
	v_or_b32_e32 v8, 17, v19
	v_cmp_ge_i32_e32 vcc, v18, v8
	v_mov_b32_e32 v8, 0
	v_mov_b32_e32 v15, 0
	s_and_saveexec_b64 s[0:1], vcc
	s_cbranch_execz .LBB0_551
	s_waitcnt lgkmcnt(0)
	v_mov_b32_e32 v15, v209
	s_waitcnt lgkmcnt(0)
	v_sub_f32_e32 v15, v21, v15
	v_mul_f32_e32 v15, 0x3fb8aa3b, v15
	v_exp_f32_e32 v15, v15
	s_nop 0
	v_mul_f32_e32 v15, v9, v15
.LBB0_551:
	s_or_b64 exec, exec, s[0:1]
	v_or_b32_e32 v9, 18, v19
	v_cmp_ge_i32_e32 vcc, v18, v9
	s_and_saveexec_b64 s[0:1], vcc
	s_cbranch_execz .LBB0_553
	s_waitcnt lgkmcnt(0)
	v_mov_b32_e32 v8, v210
	s_waitcnt lgkmcnt(0)
	v_sub_f32_e32 v8, v21, v8
	v_mul_f32_e32 v8, 0x3fb8aa3b, v8
	v_exp_f32_e32 v8, v8
	s_nop 0
	v_mul_f32_e32 v8, v10, v8
.LBB0_553:
	s_or_b64 exec, exec, s[0:1]
	v_or_b32_e32 v9, 19, v19
	v_cmp_ge_i32_e32 vcc, v18, v9
	v_mov_b32_e32 v9, 0
	v_mov_b32_e32 v10, 0
	s_and_saveexec_b64 s[0:1], vcc
	s_cbranch_execz .LBB0_555
	s_waitcnt lgkmcnt(0)
	v_mov_b32_e32 v10, v211
	s_waitcnt lgkmcnt(0)
	v_sub_f32_e32 v10, v21, v10
	v_mul_f32_e32 v10, 0x3fb8aa3b, v10
	v_exp_f32_e32 v10, v10
	s_nop 0
	v_mul_f32_e32 v10, v11, v10
.LBB0_555:
	s_or_b64 exec, exec, s[0:1]
	v_or_b32_e32 v11, 32, v19
	v_cmp_ge_i32_e32 vcc, v18, v11
	s_and_saveexec_b64 s[0:1], vcc
	s_cbranch_execz .LBB0_557
	s_waitcnt lgkmcnt(0)
	v_mov_b32_e32 v9, v212
	s_waitcnt lgkmcnt(0)
	v_sub_f32_e32 v9, v21, v9
	v_mul_f32_e32 v9, 0x3fb8aa3b, v9
	v_exp_f32_e32 v9, v9
	s_nop 0
	v_mul_f32_e32 v9, v4, v9
.LBB0_557:
	s_or_b64 exec, exec, s[0:1]
	v_or_b32_e32 v4, 33, v19
	v_cmp_ge_i32_e32 vcc, v18, v4
	v_mov_b32_e32 v4, 0
	v_mov_b32_e32 v11, 0
	s_and_saveexec_b64 s[0:1], vcc
	s_cbranch_execz .LBB0_559
	s_waitcnt lgkmcnt(0)
	v_mov_b32_e32 v11, v213
	s_waitcnt lgkmcnt(0)
	v_sub_f32_e32 v11, v21, v11
	v_mul_f32_e32 v11, 0x3fb8aa3b, v11
	v_exp_f32_e32 v11, v11
	s_nop 0
	v_mul_f32_e32 v11, v5, v11
.LBB0_559:
	s_or_b64 exec, exec, s[0:1]
	v_or_b32_e32 v5, 34, v19
	v_cmp_ge_i32_e32 vcc, v18, v5
	s_and_saveexec_b64 s[0:1], vcc
	s_cbranch_execz .LBB0_561
	s_waitcnt lgkmcnt(0)
	v_mov_b32_e32 v4, v214
	s_waitcnt lgkmcnt(0)
	v_sub_f32_e32 v4, v21, v4
	v_mul_f32_e32 v4, 0x3fb8aa3b, v4
	v_exp_f32_e32 v4, v4
	s_nop 0
	v_mul_f32_e32 v4, v6, v4
.LBB0_561:
	s_or_b64 exec, exec, s[0:1]
	v_or_b32_e32 v5, 35, v19
	v_cmp_ge_i32_e32 vcc, v18, v5
	v_mov_b32_e32 v5, 0
	v_mov_b32_e32 v6, 0
	s_and_saveexec_b64 s[0:1], vcc
	s_cbranch_execz .LBB0_563
	s_waitcnt lgkmcnt(0)
	v_mov_b32_e32 v6, v215
	s_waitcnt lgkmcnt(0)
	v_sub_f32_e32 v6, v21, v6
	v_mul_f32_e32 v6, 0x3fb8aa3b, v6
	v_exp_f32_e32 v6, v6
	s_nop 0
	v_mul_f32_e32 v6, v7, v6
.LBB0_563:
	s_or_b64 exec, exec, s[0:1]
	v_or_b32_e32 v7, 48, v19
	v_cmp_ge_i32_e32 vcc, v18, v7
	s_and_saveexec_b64 s[0:1], vcc
	s_cbranch_execz .LBB0_565
	s_waitcnt lgkmcnt(0)
	v_mov_b32_e32 v5, v216
	s_waitcnt lgkmcnt(0)
	v_sub_f32_e32 v5, v21, v5
	v_mul_f32_e32 v5, 0x3fb8aa3b, v5
	v_exp_f32_e32 v5, v5
	s_nop 0
	v_mul_f32_e32 v5, v0, v5
.LBB0_565:
	s_or_b64 exec, exec, s[0:1]
	v_or_b32_e32 v0, 49, v19
	v_cmp_ge_i32_e32 vcc, v18, v0
	v_mov_b32_e32 v7, 0
	v_mov_b32_e32 v24, 0
	s_and_saveexec_b64 s[0:1], vcc
	s_cbranch_execz .LBB0_567
	s_waitcnt lgkmcnt(0)
	v_mov_b32_e32 v0, v217
	s_waitcnt lgkmcnt(0)
	v_sub_f32_e32 v0, v21, v0
	v_mul_f32_e32 v0, 0x3fb8aa3b, v0
	v_exp_f32_e32 v0, v0
	s_nop 0
	v_mul_f32_e32 v24, v1, v0
.LBB0_567:
	s_or_b64 exec, exec, s[0:1]
	v_or_b32_e32 v0, 50, v19
	v_cmp_ge_i32_e32 vcc, v18, v0
	s_and_saveexec_b64 s[0:1], vcc
	s_cbranch_execz .LBB0_569
	s_waitcnt lgkmcnt(0)
	v_mov_b32_e32 v0, v218
	s_waitcnt lgkmcnt(0)
	v_sub_f32_e32 v0, v21, v0
	v_mul_f32_e32 v0, 0x3fb8aa3b, v0
	v_exp_f32_e32 v0, v0
	s_nop 0
	v_mul_f32_e32 v7, v2, v0
.LBB0_569:
	s_or_b64 exec, exec, s[0:1]
	v_or_b32_e32 v0, 51, v19
	v_cmp_ge_i32_e32 vcc, v18, v0
	v_mov_b32_e32 v25, 0
	s_and_saveexec_b64 s[0:1], vcc
	s_cbranch_execz .LBB0_571
	s_waitcnt lgkmcnt(0)
	v_mov_b32_e32 v0, v219
	s_waitcnt lgkmcnt(0)
	v_sub_f32_e32 v0, v21, v0
	v_mul_f32_e32 v0, 0x3fb8aa3b, v0
	v_exp_f32_e32 v0, v0
	s_nop 0
	v_mul_f32_e32 v25, v3, v0

.LBB0_581:
	s_or_b64 exec, exec, s[2:3]
	s_waitcnt vmcnt(9)
	v_ashrrev_i32_e32 v16, 2, v74
	v_and_b32_e32 v28, 15, v74
	v_bfi_b32 v0, -16, v16, v74
	v_and_b32_e32 v24, 48, v74
	s_movk_i32 s2, 0x90
	v_lshrrev_b32_e32 v76, 2, v74
	s_waitcnt lgkmcnt(0)
	v_mad_u64_u32 v[0:1], s[0:1], v0, s2, v[24:25]
	v_and_b32_e32 v17, 12, v76
	v_mad_u32_u24 v26, v28, s2, v24
	ds_read_b128 v[4:7], v0 offset:9216
	s_waitcnt vmcnt(8)
	ds_read_b128 v[12:15], v0
	ds_read_b128 v[8:11], v0 offset:9280
	ds_read_b128 v[0:3], v0 offset:64
	v_and_or_b32 v27, v16, -16, v17
	ds_read_b128 v[16:19], v26 offset:9216
	ds_read_b128 v[30:33], v26 offset:9280
	s_waitcnt vmcnt(2) lgkmcnt(1)
	v_mfma_f32_16x16x32_bf16 v[20:23], v[4:7], v[16:19], 0
	v_cmp_ge_i32_e64 s[0:1], v27, v28
	v_mov_b32_e32 v29, 0
	v_lshlrev_b32_e32 v26, 2, v27
	ds_read_b128 v[204:207], v26 offset:60416
	ds_read_b128 v[208:211], v26 offset:60672
	v_mfma_f32_16x16x32_bf16 v[16:19], v[12:15], v[16:19], 0
	s_waitcnt lgkmcnt(0)
	v_mfma_f32_16x16x32_bf16 v[20:23], v[8:11], v[30:33], v[20:23]
	v_mfma_f32_16x16x32_bf16 v[16:19], v[0:3], v[30:33], v[16:19]
	v_lshlrev_b32_e32 v31, 2, v28
	ds_read_b32 v37, v31 offset:60416
	v_mov_b32_e32 v30, 0
	s_and_saveexec_b64 s[2:3], s[0:1]
	s_cbranch_execz .LBB0_583
	s_waitcnt lgkmcnt(0)
	v_mov_b32_e32 v30, v204
	s_waitcnt lgkmcnt(0)
	v_sub_f32_e32 v30, v30, v37
	v_mul_f32_e32 v30, 0x3fb8aa3b, v30
	v_exp_f32_e32 v30, v30
.LBB0_583:
	s_or_b64 exec, exec, s[2:3]
	v_cmp_gt_i32_e64 s[38:39], v27, v28
	v_mov_b32_e32 v34, 0
	s_and_saveexec_b64 s[2:3], s[38:39]
	s_cbranch_execz .LBB0_585
	s_waitcnt lgkmcnt(0)
	v_mov_b32_e32 v32, v208
	s_waitcnt lgkmcnt(0)
	v_mul_f32_e32 v20, v20, v32
	v_mul_f32_e32 v34, v30, v20
.LBB0_585:
	s_or_b64 exec, exec, s[2:3]
	v_and_b32_e32 v32, 48, v31
	v_and_b32_e32 v20, 3, v74
	v_lshl_or_b32 v33, v27, 8, v31
	v_lshl_or_b32 v20, v20, 1, v32
	ds_write_b32 v33, v34 offset:27648
	v_mul_f32_e32 v16, v16, v30
	v_or_b32_e32 v34, 1, v27
	v_cvt_pk_bf16_f32 v16, v16, s0
	v_lshl_or_b32 v38, v27, 7, v20
	v_cmp_ge_i32_e64 s[38:39], v34, v28
	ds_write_b16 v38, v16 offset:44032
	s_and_saveexec_b64 s[2:3], s[38:39]
	s_cbranch_execz .LBB0_587
	s_waitcnt lgkmcnt(0)
	v_mov_b32_e32 v16, v205
	s_waitcnt lgkmcnt(0)
	v_sub_f32_e32 v16, v16, v37
	v_mul_f32_e32 v16, 0x3fb8aa3b, v16
	v_exp_f32_e32 v29, v16
.LBB0_587:
	s_or_b64 exec, exec, s[2:3]
	v_mov_b32_e32 v30, 0
	v_mov_b32_e32 v16, 0
	s_and_saveexec_b64 s[2:3], s[0:1]
	s_cbranch_execz .LBB0_589
	s_waitcnt lgkmcnt(0)
	v_mov_b32_e32 v16, v209
	s_waitcnt lgkmcnt(0)
	v_mul_f32_e32 v16, v21, v16
	v_mul_f32_e32 v16, v29, v16
.LBB0_589:
	s_or_b64 exec, exec, s[2:3]
	v_lshl_or_b32 v35, v34, 8, v31
	ds_write_b32 v35, v16 offset:27648
	v_mul_f32_e32 v16, v17, v29
	v_or_b32_e32 v29, 2, v27
	v_cvt_pk_bf16_f32 v16, v16, s0
	v_lshl_or_b32 v39, v34, 7, v20
	v_cmp_ge_i32_e64 s[0:1], v29, v28
	ds_write_b16 v39, v16 offset:44032
	s_and_saveexec_b64 s[2:3], s[0:1]
	s_cbranch_execz .LBB0_591
	s_waitcnt lgkmcnt(0)
	v_mov_b32_e32 v16, v206
	s_waitcnt lgkmcnt(0)
	v_sub_f32_e32 v16, v16, v37
	v_mul_f32_e32 v16, 0x3fb8aa3b, v16
	v_exp_f32_e32 v30, v16
.LBB0_591:
	s_or_b64 exec, exec, s[2:3]
	v_cmp_gt_i32_e64 s[0:1], v29, v28
	v_mov_b32_e32 v16, 0
	v_mov_b32_e32 v17, 0
	s_and_saveexec_b64 s[2:3], s[0:1]
	s_cbranch_execz .LBB0_593
	s_waitcnt lgkmcnt(0)
	v_mov_b32_e32 v17, v210
	s_waitcnt lgkmcnt(0)
	v_mul_f32_e32 v17, v22, v17
	v_mul_f32_e32 v17, v30, v17
.LBB0_593:
	s_or_b64 exec, exec, s[2:3]
	v_lshl_or_b32 v36, v29, 8, v31
	ds_write_b32 v36, v17 offset:27648
	v_mul_f32_e32 v17, v18, v30
	v_or_b32_e32 v30, 3, v27
	v_cvt_pk_bf16_f32 v17, v17, s0
	v_lshl_or_b32 v40, v29, 7, v20
	v_cmp_ge_i32_e64 s[0:1], v30, v28
	ds_write_b16 v40, v17 offset:44032
	s_and_saveexec_b64 s[2:3], s[0:1]
	s_cbranch_execz .LBB0_595
	s_waitcnt lgkmcnt(0)
	v_mov_b32_e32 v16, v207
	s_waitcnt lgkmcnt(0)
	v_sub_f32_e32 v16, v16, v37
	v_mul_f32_e32 v16, 0x3fb8aa3b, v16
	v_exp_f32_e32 v16, v16
.LBB0_595:
	s_or_b64 exec, exec, s[2:3]
	v_cmp_gt_i32_e64 s[0:1], v30, v28
	v_mov_b32_e32 v44, 0
	v_mov_b32_e32 v17, 0
	s_and_saveexec_b64 s[2:3], s[0:1]
	s_cbranch_execz .LBB0_597
	s_waitcnt lgkmcnt(0)
	v_mov_b32_e32 v17, v211
	s_waitcnt lgkmcnt(0)
	v_mul_f32_e32 v17, v23, v17
	v_mul_f32_e32 v17, v16, v17
.LBB0_597:
	s_or_b64 exec, exec, s[2:3]
	v_mul_f32_e32 v16, v19, v16
	v_mul_u32_u24_e32 v18, 0x90, v28
	s_waitcnt lgkmcnt(6)
	v_lshl_or_b32 v37, v30, 8, v31
	v_cvt_pk_bf16_f32 v16, v16, s0
	v_lshl_or_b32 v41, v30, 7, v20
	ds_write_b32 v37, v17 offset:27648
	ds_write_b16 v41, v16 offset:44032
	v_add_u32_e32 v24, v18, v24
	ds_read_b128 v[16:19], v24 offset:11520
	ds_read_b128 v[46:49], v24 offset:11584
	s_waitcnt lgkmcnt(1)
	v_mfma_f32_16x16x32_bf16 v[20:23], v[4:7], v[16:19], 0
	ds_read_b32 v43, v31 offset:60480
	v_or_b32_e32 v42, 16, v28
	v_cmp_ge_i32_e64 s[0:1], v27, v42
	v_mfma_f32_16x16x32_bf16 v[16:19], v[12:15], v[16:19], 0
	s_waitcnt lgkmcnt(1)
	v_mfma_f32_16x16x32_bf16 v[20:23], v[8:11], v[46:49], v[20:23]
	v_mfma_f32_16x16x32_bf16 v[16:19], v[0:3], v[46:49], v[16:19]
	s_and_saveexec_b64 s[2:3], s[0:1]
	s_cbranch_execz .LBB0_599
	s_waitcnt lgkmcnt(0)
	v_mov_b32_e32 v44, v204
	s_waitcnt lgkmcnt(0)
	v_sub_f32_e32 v44, v44, v43
	v_mul_f32_e32 v44, 0x3fb8aa3b, v44
	v_exp_f32_e32 v44, v44
.LBB0_599:
	s_or_b64 exec, exec, s[2:3]
	v_cmp_gt_i32_e64 s[38:39], v27, v42
	v_mov_b32_e32 v45, 0
	v_mov_b32_e32 v46, 0
	s_and_saveexec_b64 s[2:3], s[38:39]
	s_cbranch_execz .LBB0_601
	s_waitcnt lgkmcnt(0)
	v_mov_b32_e32 v46, v208
	s_waitcnt lgkmcnt(0)
	v_mul_f32_e32 v20, v20, v46
	v_mul_f32_e32 v46, v44, v20
.LBB0_601:
	s_or_b64 exec, exec, s[2:3]
	v_mul_f32_e32 v16, v16, v44
	v_cvt_pk_bf16_f32 v16, v16, s0
	v_cmp_ge_i32_e64 s[38:39], v34, v42
	ds_write_b32 v33, v46 offset:27712
	ds_write_b16 v38, v16 offset:44040
	s_and_saveexec_b64 s[2:3], s[38:39]
	s_cbranch_execz .LBB0_603
	s_waitcnt lgkmcnt(0)
	v_mov_b32_e32 v16, v205
	s_waitcnt lgkmcnt(0)
	v_sub_f32_e32 v16, v16, v43
	v_mul_f32_e32 v16, 0x3fb8aa3b, v16
	v_exp_f32_e32 v45, v16
.LBB0_603:
	s_or_b64 exec, exec, s[2:3]
	v_mov_b32_e32 v16, 0
	v_mov_b32_e32 v20, 0
	s_and_saveexec_b64 s[2:3], s[0:1]
	s_cbranch_execz .LBB0_605
	s_waitcnt lgkmcnt(0)
	v_mov_b32_e32 v20, v209
	s_waitcnt lgkmcnt(0)
	v_mul_f32_e32 v20, v21, v20
	v_mul_f32_e32 v20, v45, v20
.LBB0_605:
	s_or_b64 exec, exec, s[2:3]
	v_mul_f32_e32 v17, v17, v45
	v_cvt_pk_bf16_f32 v17, v17, s0
	v_cmp_ge_i32_e64 s[0:1], v29, v42
	ds_write_b32 v35, v20 offset:27712
	ds_write_b16 v39, v17 offset:44040
	s_and_saveexec_b64 s[2:3], s[0:1]
	s_cbranch_execz .LBB0_607
	s_waitcnt lgkmcnt(0)
	v_mov_b32_e32 v16, v206
	s_waitcnt lgkmcnt(0)
	v_sub_f32_e32 v16, v16, v43
	v_mul_f32_e32 v16, 0x3fb8aa3b, v16
	v_exp_f32_e32 v16, v16
.LBB0_607:
	s_or_b64 exec, exec, s[2:3]
	v_cmp_gt_i32_e64 s[0:1], v29, v42
	v_mov_b32_e32 v17, 0
	v_mov_b32_e32 v20, 0
	s_and_saveexec_b64 s[2:3], s[0:1]
	s_cbranch_execz .LBB0_609
	s_waitcnt lgkmcnt(0)
	v_mov_b32_e32 v20, v210
	s_waitcnt lgkmcnt(0)
	v_mul_f32_e32 v20, v22, v20
	v_mul_f32_e32 v20, v16, v20
.LBB0_609:
	s_or_b64 exec, exec, s[2:3]
	v_mul_f32_e32 v16, v18, v16
	v_cvt_pk_bf16_f32 v16, v16, s0
	v_cmp_ge_i32_e64 s[0:1], v30, v42
	ds_write_b32 v36, v20 offset:27712
	ds_write_b16 v40, v16 offset:44040
	s_and_saveexec_b64 s[2:3], s[0:1]
	s_cbranch_execz .LBB0_611
	s_waitcnt lgkmcnt(0)
	v_mov_b32_e32 v16, v207
	s_waitcnt lgkmcnt(0)
	v_sub_f32_e32 v16, v16, v43
	v_mul_f32_e32 v16, 0x3fb8aa3b, v16
	v_exp_f32_e32 v17, v16
.LBB0_611:
	s_or_b64 exec, exec, s[2:3]
	v_cmp_gt_i32_e64 s[0:1], v30, v42
	v_mov_b32_e32 v42, 0
	v_mov_b32_e32 v16, 0
	s_and_saveexec_b64 s[2:3], s[0:1]
	s_cbranch_execz .LBB0_613
	s_waitcnt lgkmcnt(0)
	v_mov_b32_e32 v16, v211
	s_waitcnt lgkmcnt(0)
	v_mul_f32_e32 v16, v23, v16
	v_mul_f32_e32 v16, v17, v16
.LBB0_613:
	s_or_b64 exec, exec, s[2:3]
	ds_write_b32 v37, v16 offset:27712
	v_mul_f32_e32 v16, v19, v17
	v_cvt_pk_bf16_f32 v16, v16, s0
	ds_write_b16 v41, v16 offset:44040
	ds_read_b128 v[16:19], v24 offset:13824
	ds_read_b128 v[44:47], v24 offset:13888
	ds_read_b32 v39, v31 offset:60544
	v_or_b32_e32 v38, 32, v28
	s_waitcnt lgkmcnt(2)
	v_mfma_f32_16x16x32_bf16 v[20:23], v[4:7], v[16:19], 0
	v_cmp_ge_i32_e64 s[0:1], v27, v38
	v_mfma_f32_16x16x32_bf16 v[16:19], v[12:15], v[16:19], 0
	s_waitcnt lgkmcnt(1)
	v_mfma_f32_16x16x32_bf16 v[20:23], v[8:11], v[44:47], v[20:23]
	v_mfma_f32_16x16x32_bf16 v[16:19], v[0:3], v[44:47], v[16:19]
	s_and_saveexec_b64 s[2:3], s[0:1]
	s_cbranch_execz .LBB0_615
	s_waitcnt lgkmcnt(0)
	v_mov_b32_e32 v40, v204
	s_waitcnt lgkmcnt(0)
	v_sub_f32_e32 v40, v40, v39
	v_mul_f32_e32 v40, 0x3fb8aa3b, v40
	v_exp_f32_e32 v42, v40
.LBB0_615:
	s_or_b64 exec, exec, s[2:3]
	v_cmp_gt_i32_e64 s[38:39], v27, v38
	v_mov_b32_e32 v41, 0
	v_mov_b32_e32 v43, 0
	s_and_saveexec_b64 s[2:3], s[38:39]
	s_cbranch_execz .LBB0_617
	s_waitcnt lgkmcnt(0)
	v_mov_b32_e32 v40, v208
	s_waitcnt lgkmcnt(0)
	v_mul_f32_e32 v20, v20, v40
	v_mul_f32_e32 v43, v42, v20
.LBB0_617:
	s_or_b64 exec, exec, s[2:3]
	v_and_b32_e32 v40, 35, v38
	v_lshlrev_b32_e32 v20, 6, v27
	v_lshl_add_u32 v40, v40, 1, v32
	v_mul_f32_e32 v16, v16, v42
	v_cvt_pk_bf16_f32 v16, v16, s0
	v_lshl_add_u32 v42, v20, 1, v40
	v_cmp_ge_i32_e64 s[38:39], v34, v38
	ds_write_b32 v33, v43 offset:27776
	ds_write_b16 v42, v16 offset:44032
	s_and_saveexec_b64 s[2:3], s[38:39]
	s_cbranch_execz .LBB0_619
	s_waitcnt lgkmcnt(0)
	v_mov_b32_e32 v16, v205
	s_waitcnt lgkmcnt(0)
	v_sub_f32_e32 v16, v16, v39
	v_mul_f32_e32 v16, 0x3fb8aa3b, v16
	v_exp_f32_e32 v41, v16
.LBB0_619:
	s_or_b64 exec, exec, s[2:3]
	v_mov_b32_e32 v42, 0
	v_mov_b32_e32 v43, 0
	s_and_saveexec_b64 s[2:3], s[0:1]
	s_cbranch_execz .LBB0_621
	s_waitcnt lgkmcnt(0)
	v_mov_b32_e32 v16, v209
	s_waitcnt lgkmcnt(0)
	v_mul_f32_e32 v16, v21, v16
	v_mul_f32_e32 v43, v41, v16
.LBB0_621:
	s_or_b64 exec, exec, s[2:3]
	v_lshlrev_b32_e32 v16, 6, v34
	v_mul_f32_e32 v17, v17, v41
	v_cvt_pk_bf16_f32 v17, v17, s0
	v_lshl_add_u32 v21, v16, 1, v40
	v_cmp_ge_i32_e64 s[0:1], v29, v38
	ds_write_b32 v35, v43 offset:27776
	ds_write_b16 v21, v17 offset:44032
	s_and_saveexec_b64 s[2:3], s[0:1]
	s_cbranch_execz .LBB0_623
	s_waitcnt lgkmcnt(0)
	v_mov_b32_e32 v17, v206
	s_waitcnt lgkmcnt(0)
	v_sub_f32_e32 v17, v17, v39
	v_mul_f32_e32 v17, 0x3fb8aa3b, v17
	v_exp_f32_e32 v42, v17
.LBB0_623:
	s_or_b64 exec, exec, s[2:3]
	v_cmp_gt_i32_e64 s[0:1], v29, v38
	v_mov_b32_e32 v41, 0
	v_mov_b32_e32 v21, 0
	s_and_saveexec_b64 s[2:3], s[0:1]
	s_cbranch_execz .LBB0_625
	s_waitcnt lgkmcnt(0)
	v_mov_b32_e32 v17, v210
	s_waitcnt lgkmcnt(0)
	v_mul_f32_e32 v17, v22, v17
	v_mul_f32_e32 v21, v42, v17
.LBB0_625:
	s_or_b64 exec, exec, s[2:3]
	v_lshlrev_b32_e32 v17, 6, v29
	v_mul_f32_e32 v18, v18, v42
	ds_write_b32 v36, v21 offset:27776
	v_cvt_pk_bf16_f32 v18, v18, s0
	v_lshl_add_u32 v21, v17, 1, v40
	v_cmp_ge_i32_e64 s[0:1], v30, v38
	ds_write_b16 v21, v18 offset:44032
	s_and_saveexec_b64 s[2:3], s[0:1]
	s_cbranch_execz .LBB0_627
	s_waitcnt lgkmcnt(0)
	v_mov_b32_e32 v18, v207
	s_waitcnt lgkmcnt(0)
	v_sub_f32_e32 v18, v18, v39
	v_mul_f32_e32 v18, 0x3fb8aa3b, v18
	v_exp_f32_e32 v41, v18
.LBB0_627:
	s_or_b64 exec, exec, s[2:3]
	v_cmp_gt_i32_e64 s[0:1], v30, v38
	v_mov_b32_e32 v21, 0
	v_mov_b32_e32 v22, 0
	s_and_saveexec_b64 s[2:3], s[0:1]
	s_cbranch_execz .LBB0_629
	s_waitcnt lgkmcnt(0)
	v_mov_b32_e32 v18, v211
	s_waitcnt lgkmcnt(0)
	v_mul_f32_e32 v18, v23, v18
	v_mul_f32_e32 v22, v41, v18
.LBB0_629:
	s_or_b64 exec, exec, s[2:3]
	v_lshlrev_b32_e32 v18, 6, v30
	v_mul_f32_e32 v19, v19, v41
	ds_write_b32 v37, v22 offset:27776
	v_cvt_pk_bf16_f32 v19, v19, s0
	v_lshl_add_u32 v22, v18, 1, v40
	ds_write_b16 v22, v19 offset:44032
	s_waitcnt lgkmcnt(8)
	ds_read_b128 v[38:41], v24 offset:16128
	ds_read_b32 v19, v31 offset:60608
	s_waitcnt lgkmcnt(1)
	v_mfma_f32_16x16x32_bf16 v[4:7], v[4:7], v[38:41], 0
	v_mfma_f32_16x16x32_bf16 v[12:15], v[12:15], v[38:41], 0
	ds_read_b128 v[38:41], v24 offset:16192
	s_waitcnt lgkmcnt(0)
	v_mfma_f32_16x16x32_bf16 v[4:7], v[8:11], v[38:41], v[4:7]
	v_or_b32_e32 v8, 48, v28
	v_cmp_ge_i32_e64 s[0:1], v27, v8
	v_mfma_f32_16x16x32_bf16 v[0:3], v[0:3], v[38:41], v[12:15]
	s_and_saveexec_b64 s[2:3], s[0:1]
	s_cbranch_execz .LBB0_631
	s_waitcnt lgkmcnt(0)
	v_mov_b32_e32 v9, v204
	s_waitcnt lgkmcnt(0)
	v_sub_f32_e32 v9, v9, v19
	v_mul_f32_e32 v9, 0x3fb8aa3b, v9
	v_exp_f32_e32 v21, v9
.LBB0_631:
	s_or_b64 exec, exec, s[2:3]
	v_cmp_gt_i32_e64 s[38:39], v27, v8
	v_mov_b32_e32 v9, 0
	v_mov_b32_e32 v10, 0
	s_and_saveexec_b64 s[2:3], s[38:39]
	s_cbranch_execz .LBB0_633
	s_waitcnt lgkmcnt(0)
	v_mov_b32_e32 v10, v208
	s_waitcnt lgkmcnt(0)
	v_mul_f32_e32 v4, v4, v10
	v_mul_f32_e32 v10, v21, v4
.LBB0_633:
	s_or_b64 exec, exec, s[2:3]
	v_and_b32_e32 v4, 35, v8
	v_lshl_add_u32 v4, v4, 1, v32
	v_mul_f32_e32 v0, v0, v21
	ds_write_b32 v33, v10 offset:27840
	v_cvt_pk_bf16_f32 v0, v0, s0
	v_lshl_add_u32 v10, v20, 1, v4
	v_cmp_ge_i32_e64 s[38:39], v34, v8
	ds_write_b16 v10, v0 offset:44040
	s_and_saveexec_b64 s[2:3], s[38:39]
	s_cbranch_execz .LBB0_635
	s_waitcnt lgkmcnt(0)
	v_mov_b32_e32 v0, v205
	s_waitcnt lgkmcnt(0)
	v_sub_f32_e32 v0, v0, v19
	v_mul_f32_e32 v0, 0x3fb8aa3b, v0
	v_exp_f32_e32 v9, v0
.LBB0_635:
	s_or_b64 exec, exec, s[2:3]
	v_mov_b32_e32 v0, 0
	v_mov_b32_e32 v10, 0
	s_and_saveexec_b64 s[2:3], s[0:1]
	s_cbranch_execz .LBB0_637
	s_waitcnt lgkmcnt(0)
	v_mov_b32_e32 v10, v209
	s_waitcnt lgkmcnt(0)
	v_mul_f32_e32 v5, v5, v10
	v_mul_f32_e32 v10, v9, v5
.LBB0_637:
	s_or_b64 exec, exec, s[2:3]
	v_mul_f32_e32 v1, v1, v9
	v_cvt_pk_bf16_f32 v1, v1, s0
	v_lshl_add_u32 v5, v16, 1, v4
	v_cmp_ge_i32_e64 s[0:1], v29, v8
	ds_write_b32 v35, v10 offset:27840
	ds_write_b16 v5, v1 offset:44040
	s_and_saveexec_b64 s[2:3], s[0:1]
	s_cbranch_execz .LBB0_639
	s_waitcnt lgkmcnt(0)
	v_mov_b32_e32 v0, v206
	s_waitcnt lgkmcnt(0)
	v_sub_f32_e32 v0, v0, v19
	v_mul_f32_e32 v0, 0x3fb8aa3b, v0
	v_exp_f32_e32 v0, v0
.LBB0_639:
	s_or_b64 exec, exec, s[2:3]
	v_cmp_gt_i32_e64 s[0:1], v29, v8
	v_mov_b32_e32 v1, 0
	v_mov_b32_e32 v5, 0
	s_and_saveexec_b64 s[2:3], s[0:1]
	s_cbranch_execz .LBB0_641
	s_waitcnt lgkmcnt(0)
	v_mov_b32_e32 v5, v210
	s_waitcnt lgkmcnt(0)
	v_mul_f32_e32 v5, v6, v5
	v_mul_f32_e32 v5, v0, v5
.LBB0_641:
	s_or_b64 exec, exec, s[2:3]
	v_mul_f32_e32 v0, v2, v0
	v_cvt_pk_bf16_f32 v0, v0, s0
	v_lshl_add_u32 v2, v17, 1, v4
	v_cmp_ge_i32_e64 s[0:1], v30, v8
	ds_write_b32 v36, v5 offset:27840
	ds_write_b16 v2, v0 offset:44040
	s_and_saveexec_b64 s[2:3], s[0:1]
	s_cbranch_execz .LBB0_643
	s_waitcnt lgkmcnt(0)
	v_mov_b32_e32 v0, v207
	s_waitcnt lgkmcnt(0)
	v_sub_f32_e32 v0, v0, v19
	v_mul_f32_e32 v0, 0x3fb8aa3b, v0
	v_exp_f32_e32 v1, v0
.LBB0_643:
	s_or_b64 exec, exec, s[2:3]
	v_cmp_gt_i32_e64 s[0:1], v30, v8
	v_mov_b32_e32 v0, 0
	s_and_saveexec_b64 s[2:3], s[0:1]
	s_cbranch_execz .LBB0_645
	s_waitcnt lgkmcnt(0)
	v_mov_b32_e32 v0, v211
	s_waitcnt lgkmcnt(0)
	v_mul_f32_e32 v0, v7, v0
	v_mul_f32_e32 v0, v1, v0
